# attention: remaining copies in front of exps replaced by the exps themselves; zero-seed add of the row sum dropped
# baseline (speedup 1.0000x reference)
.LBB0_1004:
	v_mfma_f32_32x32x16_bf16 v[68:83], v[246:249], v[250:253], 0
	v_mfma_f32_32x32x16_bf16 v[68:83], v[136:139], v[100:103], v[68:83]
	v_add_u32_e32 v2, s45, v189
	ds_read_b128 v[184:187], v2 offset:96
	ds_read_b128 v[210:213], v2 offset:128
	ds_read_b128 v[214:217], v2 offset:6752
	ds_read_b128 v[218:221], v2 offset:160
	ds_read_b128 v[222:225], v2 offset:6784
	ds_read_b128 v[226:229], v2 offset:6816
	v_add_u32_e32 v2, s39, v200
	ds_read_b128 v[176:179], v2 offset:53248
	ds_read_b128 v[164:167], v2 offset:53280
	ds_read_b128 v[230:233], v2 offset:57856
	ds_read_b128 v[238:241], v2 offset:57888
	ds_read_b128 v[160:163], v2 offset:53312
	ds_read_b128 v[156:159], v2 offset:53344
	ds_read_b128 v[242:245], v2 offset:57920
	ds_read_b128 v[152:155], v2 offset:57952
	v_mfma_f32_32x32x16_bf16 v[84:99], v[246:249], v[250:253], 0
	v_mfma_f32_32x32x16_bf16 v[84:99], v[132:135], v[100:103], v[84:99]
	v_exp_f32_e32 v52, v52
	v_exp_f32_e32 v183, v36
	v_exp_f32_e32 v132, v53
	v_exp_f32_e32 v53, v54
	v_mfma_f32_32x32x16_bf16 v[68:83], v[144:147], v[104:107], v[68:83]
	v_exp_f32_e32 v54, v38
	v_exp_f32_e32 v36, v55
	v_exp_f32_e32 v55, v56
	v_exp_f32_e32 v56, v40
	v_mfma_f32_32x32x16_bf16 v[84:99], v[128:131], v[104:107], v[84:99]
	v_exp_f32_e32 v40, v39
	v_exp_f32_e32 v38, v57
	v_exp_f32_e32 v57, v58
	v_exp_f32_e32 v58, v41
	v_mfma_f32_32x32x16_bf16 v[68:83], v[140:143], v[108:111], v[68:83]
	v_add_u32_e32 v181, s44, v189
	ds_read_b128 v[144:147], v181
	ds_read_b128 v[172:175], v181 offset:32
	ds_read_b128 v[136:139], v181 offset:6656
	ds_read_b128 v[168:171], v181 offset:64
	ds_read_b128 v[148:151], v181 offset:6688
	ds_read_b128 v[140:143], v181 offset:6720
	v_exp_f32_e32 v2, v37
	v_mfma_f32_32x32x16_bf16 v[84:99], v[124:127], v[108:111], v[84:99]
	v_exp_f32_e32 v124, v59
	v_exp_f32_e32 v41, v60
	v_add_f32_e32 v133, v52, v183
	v_add_f32_e32 v37, v53, v54
	s_waitcnt lgkmcnt(14)
	v_mfma_f32_32x32x16_bf16 v[68:83], v[214:217], v[112:115], v[68:83]
	v_exp_f32_e32 v214, v42
	v_exp_f32_e32 v59, v44
	v_exp_f32_e32 v60, v43
	v_exp_f32_e32 v126, v61
	v_mfma_f32_32x32x16_bf16 v[84:99], v[184:187], v[112:115], v[84:99]
	v_exp_f32_e32 v61, v62
	v_exp_f32_e32 v62, v45
	v_exp_f32_e32 v128, v63
	v_exp_f32_e32 v63, v64
	v_mfma_f32_32x32x16_bf16 v[68:83], v[222:225], v[116:119], v[68:83]
	v_exp_f32_e32 v216, v48
	v_exp_f32_e32 v64, v47
	v_exp_f32_e32 v130, v65
	v_mfma_f32_32x32x16_bf16 v[84:99], v[210:213], v[116:119], v[84:99]
	v_exp_f32_e32 v65, v66
	v_exp_f32_e32 v215, v46
	v_exp_f32_e32 v185, v50
	v_mfma_f32_32x32x16_bf16 v[68:83], v[226:229], v[120:123], v[68:83]
	v_exp_f32_e32 v66, v49
	v_exp_f32_e32 v134, v67
	v_add_f32_e32 v39, v55, v56
	v_add_f32_e32 v125, v57, v214
	v_mfma_f32_32x32x16_bf16 v[84:99], v[218:221], v[120:123], v[84:99]
	v_add_f32_e32 v127, v41, v59
	v_add_f32_e32 v129, v61, v215
	v_add_f32_e32 v131, v63, v216
	v_add_f32_e32 v135, v65, v185
	v_exp_f32_e32 v184, v51
	v_cvt_pk_bf16_f32 v42, v52, v132
	v_cvt_pk_bf16_f32 v43, v53, v36
	v_cvt_pk_bf16_f32 v44, v55, v38
	v_cvt_pk_bf16_f32 v45, v57, v124
	v_cvt_pk_bf16_f32 v46, v41, v126
	v_cvt_pk_bf16_f32 v47, v61, v128
	v_cvt_pk_bf16_f32 v48, v63, v130
	v_cvt_pk_bf16_f32 v49, v65, v134
	v_cvt_pk_bf16_f32 v50, v183, v2
	v_cvt_pk_bf16_f32 v51, v54, v40
	v_cvt_pk_bf16_f32 v52, v56, v58
	v_cvt_pk_bf16_f32 v53, v214, v60
	v_cvt_pk_bf16_f32 v54, v59, v62
	v_cvt_pk_bf16_f32 v55, v215, v64
	v_cvt_pk_bf16_f32 v56, v216, v66
	v_cvt_pk_bf16_f32 v57, v185, v184
	s_add_i32 s14, s46, 5
	s_min_u32 s14, s14, s37
	s_add_i32 s15, s46, 3
	s_min_u32 s46, s15, s37
	s_mulk_i32 s14, 0x3000
	s_add_u32 s14, s10, s14
	s_addc_u32 s15, s11, 0
	s_lshl_b32 s46, s46, 13
	s_add_u32 s46, s12, s46
	s_addc_u32 s47, s13, 0
	s_add_i32 m0, s22, s45
	s_and_b64 s[48:49], s[4:5], exec
	s_waitcnt vmcnt(3) lgkmcnt(0)
	s_barrier
	v_lshl_add_u64 v[186:187], s[14:15], 0, v[190:191]
	s_cselect_b32 s15, s15, s47
	s_cselect_b32 s14, s14, s46
	global_load_lds_dwordx4 v[186:187], off
	v_lshl_add_u64 v[186:187], s[14:15], 0, v[192:193]
	s_cselect_b32 s14, s45, s39
	s_add_i32 m0, s21, s14
	s_add_i32 s14, s23, s39
	global_load_lds_dwordx4 v[186:187], off
	v_lshl_add_u64 v[186:187], s[46:47], 0, v[194:195]
	s_add_i32 m0, s14, 0xd000
	s_nop 0
	global_load_lds_dwordx4 v[186:187], off
	v_mfma_f32_32x32x16_bf16 v[4:19], v[42:45], v[230:233], v[4:19]
	v_max3_f32 v41, v84, v68, v85
	v_max3_f32 v59, v92, v76, v93
	v_add_f32_e32 v132, v132, v2
	v_max3_f32 v41, v41, v69, v86
	v_max3_f32 v59, v59, v77, v94
	s_nop 0
	v_max3_f32 v41, v41, v70, v87
	v_mfma_f32_32x32x16_bf16 v[20:35], v[42:45], v[176:179], v[20:35]
	v_max3_f32 v41, v41, v71, v88
	v_max3_f32 v59, v59, v78, v95
	v_max3_f32 v41, v41, v72, v89
	v_max3_f32 v59, v59, v79, v96
	s_nop 0
	v_max3_f32 v41, v41, v73, v90
	v_mfma_f32_32x32x16_bf16 v[4:19], v[46:49], v[238:241], v[4:19]
	v_max3_f32 v183, v41, v74, v91
	v_add_f32_e32 v41, v132, v133
	v_max3_f32 v59, v59, v80, v97
	v_add_f32_e64 v36, v36, v40
	v_add_f32_e64 v37, v37, v41
	v_max3_f32 v59, v59, v81, v98
	v_mfma_f32_32x32x16_bf16 v[20:35], v[46:49], v[164:167], v[20:35]
	v_max3_f32 v186, v59, v82, v99
	v_add_f32_e32 v59, v36, v37
	v_add_f32_e32 v36, v38, v58
	v_add_f32_e32 v37, v39, v59
	v_add_f32_e32 v61, v36, v37
	v_add_f32_e32 v36, v124, v60
	v_add_f32_e32 v37, v125, v61
	v_mfma_f32_32x32x16_bf16 v[4:19], v[50:53], v[242:245], v[4:19]
	v_add_f32_e32 v63, v36, v37
	v_add_f32_e32 v36, v126, v62
	v_add_f32_e32 v37, v127, v63
	v_add_f32_e32 v65, v36, v37
	v_add_f32_e32 v36, v128, v64
	v_add_f32_e32 v37, v129, v65
	v_mfma_f32_32x32x16_bf16 v[20:35], v[50:53], v[160:163], v[20:35]
	v_add_f32_e32 v67, v36, v37
	v_add_f32_e32 v36, v130, v66
	v_add_f32_e32 v37, v131, v67
	v_add_f32_e32 v185, v36, v37
	v_add_f32_e32 v36, v134, v184
	v_add_f32_e32 v37, v135, v185
	v_mfma_f32_32x32x16_bf16 v[20:35], v[54:57], v[156:159], v[20:35]
	v_add_f32_e32 v2, v36, v37
	v_max3_f32 v36, v183, v75, v186
	v_add_f32_e32 v2, v209, v2
	v_max3_f32 v36, v36, v83, v36
	s_nop 0
	v_mov_b32_e32 v37, v36
	v_mov_b32_e32 v38, v36
	v_mfma_f32_32x32x16_bf16 v[4:19], v[54:57], v[152:155], v[4:19]
	s_nop 0
	v_permlane32_swap_b32_e32 v37, v38
	v_max3_f32 v36, v37, v38, v36
	s_nop 0
	v_cmp_lt_f32_e32 vcc, s56, v36
	s_cbranch_vccz .LBB0_1008
	s_nop 0
	v_add_f32_e32 v210, v180, v36
	v_cvt_pk_bf16_f32 v210, v210, v210
	v_lshlrev_b32_e32 v210, 16, v210
	v_cndmask_b32_e32 v210, v180, v210, vcc
	v_sub_f32_e32 v36, v180, v210
	v_sub_f32_e32 v186, v210, v180
	v_xor_b32_e32 v250, 0x80000000, v210
	v_min_f32_e32 v36, 0, v36
	v_lshrrev_b32_e32 v250, 16, v250
	v_exp_f32_e32 v36, v36
	v_cndmask_b32_e64 v250, 0, v250, s[2:3]
	s_and_saveexec_b64 s[14:15], s[2:3]
	ds_write_b32 v202, v36
	s_or_b64 exec, exec, s[14:15]
	v_mul_f32_e32 v2, v2, v36
	ds_read_b32 v36, v1
	ds_read_b32 v37, v1 offset:4
	ds_read_b32 v38, v1 offset:8
	ds_read_b32 v39, v1 offset:12
	ds_read_b32 v40, v1 offset:32
	ds_read_b32 v41, v1 offset:36
	ds_read_b32 v42, v1 offset:40
	ds_read_b32 v43, v1 offset:44
	ds_read_b32 v44, v1 offset:64
	ds_read_b32 v45, v1 offset:68
	ds_read_b32 v46, v1 offset:72
	ds_read_b32 v47, v1 offset:76
	ds_read_b32 v48, v1 offset:96
	ds_read_b32 v49, v1 offset:100
	ds_read_b32 v50, v1 offset:104
	ds_read_b32 v51, v1 offset:108
	s_waitcnt lgkmcnt(0)
	v_pk_mul_f32 v[20:21], v[20:21], v[36:37]
	v_pk_mul_f32 v[22:23], v[22:23], v[38:39]
	v_pk_mul_f32 v[24:25], v[24:25], v[40:41]
	v_pk_mul_f32 v[26:27], v[26:27], v[42:43]
	v_pk_mul_f32 v[28:29], v[28:29], v[44:45]
	v_pk_mul_f32 v[30:31], v[30:31], v[46:47]
	v_pk_mul_f32 v[32:33], v[32:33], v[48:49]
	v_pk_mul_f32 v[34:35], v[34:35], v[50:51]
	v_pk_mul_f32 v[4:5], v[4:5], v[36:37]
	v_pk_mul_f32 v[6:7], v[6:7], v[38:39]
	v_pk_mul_f32 v[8:9], v[8:9], v[40:41]
	v_pk_mul_f32 v[10:11], v[10:11], v[42:43]
	v_pk_mul_f32 v[12:13], v[12:13], v[44:45]
	v_pk_mul_f32 v[14:15], v[14:15], v[46:47]
	v_pk_mul_f32 v[16:17], v[16:17], v[48:49]
	v_pk_mul_f32 v[18:19], v[18:19], v[50:51]
	v_sub_f32_e32 v68, v68, v186
	v_sub_f32_e32 v69, v69, v186
	v_sub_f32_e32 v70, v70, v186
	v_sub_f32_e32 v71, v71, v186
	v_sub_f32_e32 v72, v72, v186
	v_sub_f32_e32 v73, v73, v186
	v_sub_f32_e32 v74, v74, v186
	v_sub_f32_e32 v75, v75, v186
	v_sub_f32_e32 v76, v76, v186
	v_sub_f32_e32 v77, v77, v186
	v_sub_f32_e32 v78, v78, v186
	v_sub_f32_e32 v79, v79, v186
	v_sub_f32_e32 v80, v80, v186
	v_sub_f32_e32 v81, v81, v186
	v_sub_f32_e32 v82, v82, v186
	v_sub_f32_e32 v83, v83, v186
	v_sub_f32_e32 v84, v84, v186
	v_sub_f32_e32 v85, v85, v186
	v_sub_f32_e32 v86, v86, v186
	v_sub_f32_e32 v87, v87, v186
	v_sub_f32_e32 v88, v88, v186
	v_sub_f32_e32 v89, v89, v186
	v_sub_f32_e32 v90, v90, v186
	v_sub_f32_e32 v91, v91, v186
	v_sub_f32_e32 v92, v92, v186
	v_sub_f32_e32 v93, v93, v186
	v_sub_f32_e32 v94, v94, v186
	v_sub_f32_e32 v95, v95, v186
	v_sub_f32_e32 v96, v96, v186
	v_sub_f32_e32 v97, v97, v186
	v_sub_f32_e32 v98, v98, v186
	v_sub_f32_e32 v99, v99, v186
	s_mov_b32 s56, 0x41000000
	s_branch .LBB0_1009

.LBB0_1009:
	v_mfma_f32_32x32x16_bf16 v[36:51], v[246:249], v[250:253], 0
	v_mfma_f32_32x32x16_bf16 v[36:51], v[136:139], v[100:103], v[36:51]
	v_add_u32_e32 v52, s43, v200
	ds_read_b128 v[212:215], v181 offset:96
	ds_read_b128 v[216:219], v181 offset:128
	ds_read_b128 v[220:223], v181 offset:6752
	ds_read_b128 v[224:227], v181 offset:160
	ds_read_b128 v[228:231], v181 offset:6784
	ds_read_b128 v[238:241], v181 offset:6816
	ds_read_b128 v[160:163], v52 offset:53248
	ds_read_b128 v[164:167], v52 offset:53280
	ds_read_b128 v[184:187], v52 offset:57856
	ds_read_b128 v[180:183], v52 offset:57888
	ds_read_b128 v[156:159], v52 offset:53312
	ds_read_b128 v[152:155], v52 offset:53344
	v_add_u32_e32 v209, s41, v189
	v_mfma_f32_32x32x16_bf16 v[36:51], v[148:151], v[104:107], v[36:51]
	ds_read_b128 v[176:179], v52 offset:57920
	ds_read_b128 v[148:151], v52 offset:57952
	v_exp_f32_e32 v211, v84
	v_exp_f32_e32 v232, v68
	v_exp_f32_e32 v233, v85
	v_mfma_f32_32x32x16_bf16 v[52:67], v[246:249], v[250:253], 0
	v_mfma_f32_32x32x16_bf16 v[52:67], v[144:147], v[100:103], v[52:67]
	v_exp_f32_e32 v235, v69
	v_add_f32_e32 v68, v211, v232
	v_add_f32_e32 v69, v233, v235
	v_add_f32_e32 v68, v69, v68
	v_mfma_f32_32x32x16_bf16 v[52:67], v[172:175], v[104:107], v[52:67]
	v_exp_f32_e32 v173, v70
	v_exp_f32_e32 v172, v86
	v_exp_f32_e32 v174, v87
	v_exp_f32_e32 v175, v71
	v_add_f32_e32 v69, v172, v173
	v_add_f32_e32 v68, v69, v68
	v_mfma_f32_32x32x16_bf16 v[52:67], v[168:171], v[108:111], v[52:67]
	v_add_f32_e32 v69, v174, v175
	v_add_f32_e32 v168, v69, v68
	v_exp_f32_e32 v71, v88
	v_exp_f32_e32 v85, v72
	v_exp_f32_e32 v70, v89
	v_exp_f32_e32 v84, v73
	v_exp_f32_e32 v73, v90
	v_exp_f32_e32 v87, v74
	v_exp_f32_e32 v72, v91
	v_exp_f32_e32 v86, v75
	v_pk_add_f32 v[68:69], v[70:71], v[84:85]
	v_mfma_f32_32x32x16_bf16 v[36:51], v[140:143], v[108:111], v[36:51]
	v_add_f32_e32 v69, v69, v168
	v_add_f32_e32 v74, v68, v69
	v_add_f32_e64 v68, v72, v86
	v_add_f32_e64 v69, v73, v87
	ds_read_b128 v[132:135], v209
	ds_read_b128 v[128:131], v209 offset:32
	ds_read_b128 v[136:139], v209 offset:6656
	ds_read_b128 v[124:127], v209 offset:64
	v_add_f32_e32 v69, v69, v74
	v_add_f32_e32 v168, v68, v69
	v_exp_f32_e32 v75, v92
	v_exp_f32_e32 v89, v76
	v_exp_f32_e32 v74, v93
	v_exp_f32_e32 v88, v77
	v_exp_f32_e32 v77, v94
	s_waitcnt lgkmcnt(12)
	v_mfma_f32_32x32x16_bf16 v[36:51], v[220:223], v[112:115], v[36:51]
	v_exp_f32_e32 v91, v78
	v_exp_f32_e32 v76, v95
	v_exp_f32_e32 v90, v79
	v_pk_add_f32 v[68:69], v[74:75], v[88:89]
	ds_read_b128 v[144:147], v209 offset:6688
	ds_read_b128 v[140:143], v209 offset:6720
	v_mfma_f32_32x32x16_bf16 v[52:67], v[212:215], v[112:115], v[52:67]
	v_add_f32_e32 v69, v69, v168
	v_add_f32_e32 v78, v68, v69
	v_add_f32_e64 v68, v76, v90
	v_add_f32_e64 v69, v77, v91
	v_add_f32_e32 v69, v69, v78
	v_add_f32_e32 v168, v68, v69
	v_mfma_f32_32x32x16_bf16 v[36:51], v[228:231], v[116:119], v[36:51]
	v_exp_f32_e32 v79, v96
	v_exp_f32_e32 v93, v80
	v_exp_f32_e32 v78, v97
	v_exp_f32_e32 v92, v81
	v_mfma_f32_32x32x16_bf16 v[52:67], v[216:219], v[116:119], v[52:67]
	v_exp_f32_e32 v95, v98
	v_exp_f32_e32 v97, v82
	v_exp_f32_e32 v94, v99
	v_mfma_f32_32x32x16_bf16 v[36:51], v[238:241], v[120:123], v[36:51]
	v_exp_f32_e32 v96, v83
	v_pk_add_f32 v[68:69], v[78:79], v[92:93]
	s_nop 0
	v_add_f32_e32 v69, v69, v168
	v_add_f32_e32 v80, v68, v69
	v_pk_add_f32 v[68:69], v[94:95], v[96:97]
	v_mfma_f32_32x32x16_bf16 v[52:67], v[224:227], v[120:123], v[52:67]
	v_add_f32_e32 v69, v69, v80
	v_add_f32_e32 v68, v68, v69
	v_add_f32_e32 v209, v2, v68
	v_cvt_pk_bf16_f32 v68, v211, v233
	v_cvt_pk_bf16_f32 v69, v172, v174
	v_cvt_pk_bf16_f32 v70, v71, v70
	v_cvt_pk_bf16_f32 v71, v73, v72
	v_cvt_pk_bf16_f32 v80, v75, v74
	v_cvt_pk_bf16_f32 v81, v77, v76
	v_cvt_pk_bf16_f32 v82, v79, v78
	v_cvt_pk_bf16_f32 v83, v95, v94
	v_cvt_pk_bf16_f32 v76, v232, v235
	v_cvt_pk_bf16_f32 v77, v173, v175
	v_cvt_pk_bf16_f32 v78, v85, v84
	v_cvt_pk_bf16_f32 v79, v87, v86
	v_cvt_pk_bf16_f32 v72, v89, v88
	v_cvt_pk_bf16_f32 v73, v91, v90
	v_cvt_pk_bf16_f32 v74, v93, v92
	v_cvt_pk_bf16_f32 v75, v97, v96
	s_waitcnt vmcnt(3) lgkmcnt(0)
	s_barrier
	s_cmp_ge_u32 s42, s36
	s_cbranch_scc1 .LBB0_1011
	s_mov_b32 s14, s41
	s_mov_b32 s15, s38
	s_mov_b32 s41, s45
	s_mov_b32 s38, s44
	s_mov_b32 s44, s40
	s_mov_b32 s40, s43
	s_mov_b32 s46, s42
	s_branch .LBB0_999
